# static placement variant ix: RWKV and HGRN chains alone, RetNet chains paired with GLA chains
# speedup vs baseline: 1.0458x; 1.0458x over previous
.LBB0_285:
	s_or_b64 exec, exec, s[0:1]
	v_readlane_b32 s4, v254, 3
	v_readlane_b32 s18, v254, 17
	v_readlane_b32 s19, v254, 18
	s_add_u32 s0, s18, 0x5790000
	v_readlane_b32 s5, v254, 4
	v_readlane_b32 s6, v254, 5
	v_readlane_b32 s7, v254, 6
	v_readlane_b32 s8, v254, 7
	v_readlane_b32 s9, v254, 8
	v_readlane_b32 s10, v254, 9
	v_readlane_b32 s11, v254, 10
	v_readlane_b32 s12, v254, 11
	v_readlane_b32 s13, v254, 12
	v_readlane_b32 s14, v254, 13
	v_readlane_b32 s15, v254, 14
	v_readlane_b32 s16, v254, 15
	v_readlane_b32 s17, v254, 16
	v_writelane_b32 v254, s0, 62
	s_addc_u32 s0, s19, 0
	s_add_u32 s26, s74, 0x1000
	s_addc_u32 s27, s75, 0
	v_writelane_b32 v254, s0, 63
	s_add_u32 s0, s74, 0x1200
	s_addc_u32 s1, s75, 0
	s_mov_b32 s87, 0
	v_writelane_b32 v255, s0, 0
	v_mov_b32_e32 v28, 0
	s_movk_i32 s7, 0x1e20
	v_writelane_b32 v255, s1, 1
	s_add_u32 s0, s74, 0x1400
	s_addc_u32 s1, s75, 0
	v_writelane_b32 v255, s0, 2
	s_movk_i32 s24, 0x1000
	s_mov_b32 s90, 0xbfb8aa3b
	v_writelane_b32 v255, s1, 3
	s_add_u32 s0, s74, 0x1600
	s_addc_u32 s1, s75, 0
	v_writelane_b32 v255, s0, 4
	s_mov_b32 s91, 0x800000
	s_mov_b32 s92, 0x3f317217
	v_writelane_b32 v255, s1, 5
	s_add_u32 s0, s74, 0x1800
	s_addc_u32 s1, s75, 0
	v_writelane_b32 v255, s0, 6
	s_mov_b32 s93, 0x7f800000
	s_mov_b32 s6, 0x3e3504f3
	v_writelane_b32 v255, s1, 7
	s_add_u32 s0, s74, 0x1a00
	s_addc_u32 s1, s75, 0
	v_writelane_b32 v255, s0, 8
	s_movk_i32 s94, 0x800
	v_mov_b32_e32 v71, 0x42800000
	v_writelane_b32 v255, s1, 9
	s_add_u32 s0, s74, 0x1c00
	s_addc_u32 s1, s75, 0
	v_writelane_b32 v255, s0, 10
	v_mov_b32_e32 v72, 0x1800
	v_mov_b32_e32 v73, 0x1600
	v_writelane_b32 v255, s1, 11
	s_add_u32 s0, s74, 0x1e00
	s_addc_u32 s1, s75, 0
	v_writelane_b32 v255, s0, 12
	v_mov_b32_e32 v74, 0x3e000000
	v_mov_b32_e32 v75, 0x41b17218
	v_writelane_b32 v255, s1, 13
	s_add_u32 s0, s18, 0x4790000
	v_writelane_b32 v255, s0, 14
	s_addc_u32 s0, s19, 0
	v_writelane_b32 v255, s0, 15
	s_add_u32 s0, s18, 0x7090000
	v_writelane_b32 v255, s0, 16
	s_addc_u32 s0, s19, 0
	v_writelane_b32 v255, s0, 17
	s_add_u32 s0, s18, 0x5f90000
	v_writelane_b32 v255, s0, 18
	s_addc_u32 s0, s19, 0
	s_add_u32 s31, s18, 0x4690000
	v_writelane_b32 v255, s0, 19
	s_addc_u32 s0, s19, 0
	v_writelane_b32 v255, s0, 20
	s_add_u32 s0, s18, 0x4500000
	v_writelane_b32 v255, s0, 22
	s_addc_u32 s0, s19, 0
	v_writelane_b32 v255, s0, 24
	s_add_u32 s0, s18, 0x4400000
	v_writelane_b32 v255, s0, 26
	s_addc_u32 s0, s19, 0
	v_writelane_b32 v255, s0, 42
	s_add_i32 s3, 0, 0x10010
	s_add_i32 s0, 0, 0x3000
	v_writelane_b32 v255, s0, 44
	v_mov_b32_e32 v70, s3
	v_mov_b32_e32 v76, 0xc00
	v_mov_b32_e32 v77, 0xb00
	v_mov_b32_e32 v78, 0x1000
	s_waitcnt lgkmcnt(0)
	s_barrier
	s_mov_b32 s99, -1
	s_mov_b32 s100, 0
	s_cmp_lg_u32 s28, 0x200
	s_cbranch_scc1 .Lmap_done_0
	s_movk_i32 s100, 0x140
	s_cmp_ge_u32 s2, 0x100
	s_cbranch_scc1 .Lmap_hi_0
	s_mov_b32 s99, s2
	s_cmp_lt_u32 s2, 192
	s_cbranch_scc1 .Lmap_done_0
	s_add_u32 s99, s2, 64
	s_branch .Lmap_done_0
.Lmap_hi_0:
	s_cmp_lt_u32 s2, 448
	s_cbranch_scc1 .Lmap_done_0
	s_sub_u32 s99, s2, 256

.LBB0_1268:
	s_or_b64 exec, exec, s[0:1]
	v_readlane_b32 s52, v255, 26
	v_readlane_b32 s58, v255, 32
	v_readlane_b32 s59, v255, 33
	s_add_u32 s92, s58, 0x2000
	s_addc_u32 s93, s59, 0
	s_add_u32 s0, s58, 0x3000
	s_addc_u32 s1, s59, 0
	v_writelane_b32 v254, s0, 37
	v_readlane_b32 s53, v255, 27
	v_readlane_b32 s54, v255, 28
	v_writelane_b32 v254, s1, 38
	s_add_u32 s0, s58, 0x2200
	s_addc_u32 s1, s59, 0
	v_writelane_b32 v254, s0, 58
	v_readlane_b32 s55, v255, 29
	v_readlane_b32 s56, v255, 30
	v_writelane_b32 v254, s1, 59
	s_add_u32 s0, s58, 0x3200
	s_addc_u32 s1, s59, 0
	v_readlane_b32 s57, v255, 31
	v_readlane_b32 s60, v255, 34
	v_readlane_b32 s61, v255, 35
	v_readlane_b32 s62, v255, 36
	v_readlane_b32 s63, v255, 37
	v_readlane_b32 s64, v255, 38
	v_readlane_b32 s65, v255, 39
	v_readlane_b32 s66, v255, 40
	v_readlane_b32 s67, v255, 41
	v_writelane_b32 v255, s0, 20
	s_mov_b32 s11, 0
	v_mov_b32_e32 v28, 0
	v_writelane_b32 v255, s1, 21
	s_add_u32 s0, s58, 0x2400
	s_addc_u32 s1, s59, 0
	v_writelane_b32 v255, s0, 22
	s_movk_i32 s3, 0x1e20
	s_movk_i32 s94, 0x1000
	v_writelane_b32 v255, s1, 23
	s_add_u32 s0, s58, 0x3400
	s_addc_u32 s1, s59, 0
	v_writelane_b32 v255, s0, 24
	s_mov_b32 s95, 0xbfb8aa3b
	s_mov_b32 s52, 0x800000
	v_writelane_b32 v255, s1, 25
	s_add_u32 s0, s58, 0x2600
	s_addc_u32 s1, s59, 0
	v_writelane_b32 v254, s0, 60
	s_mov_b32 s53, 0x3f317217
	s_mov_b32 s54, 0x7f800000
	v_writelane_b32 v254, s1, 61
	s_add_u32 s0, s58, 0x3600
	s_addc_u32 s1, s59, 0
	v_writelane_b32 v255, s0, 0
	s_mov_b32 s4, 0x3e3504f3
	s_movk_i32 s55, 0x800
	v_writelane_b32 v255, s1, 1
	s_add_u32 s0, s58, 0x2800
	s_addc_u32 s1, s59, 0
	v_writelane_b32 v255, s0, 2
	v_mov_b32_e32 v73, 0x42800000
	v_mov_b32_e32 v74, 0x1800
	v_writelane_b32 v255, s1, 3
	s_add_u32 s0, s58, 0x3800
	s_addc_u32 s1, s59, 0
	v_writelane_b32 v255, s0, 4
	v_mov_b32_e32 v75, 0x1600
	v_mov_b32_e32 v76, 0x3e000000
	v_writelane_b32 v255, s1, 5
	s_add_u32 s0, s58, 0x2a00
	s_addc_u32 s1, s59, 0
	v_writelane_b32 v255, s0, 6
	v_mov_b32_e32 v77, 0x41b17218
	v_mov_b32_e32 v78, 0xc00
	v_writelane_b32 v255, s1, 7
	s_add_u32 s0, s58, 0x3a00
	s_addc_u32 s1, s59, 0
	v_writelane_b32 v255, s0, 8
	v_mov_b32_e32 v79, 0xb00
	v_mov_b32_e32 v80, 0x1000
	v_writelane_b32 v255, s1, 9
	s_add_u32 s0, s58, 0x2c00
	s_addc_u32 s1, s59, 0
	v_writelane_b32 v255, s0, 10
	s_waitcnt lgkmcnt(0)
	s_barrier
	v_writelane_b32 v255, s1, 11
	s_add_u32 s0, s58, 0x3c00
	s_addc_u32 s1, s59, 0
	s_add_u32 s96, s58, 0x2e00
	s_addc_u32 s97, s59, 0
	s_add_u32 s90, s58, 0x3e00
	v_writelane_b32 v255, s0, 12
	s_addc_u32 s91, s59, 0
	s_add_i32 s5, 0, 0x10010
	v_writelane_b32 v255, s1, 13
	v_mov_b32_e32 v72, s5
	s_mov_b32 s99, -1
	s_mov_b32 s100, 0
	s_cmp_lg_u32 s28, 0x200
	s_cbranch_scc1 .Lmap_done_1
	s_movk_i32 s100, 0x140
	s_cmp_ge_u32 s2, 0x100
	s_cbranch_scc1 .Lmap_hi_1
	s_mov_b32 s99, s2
	s_cmp_lt_u32 s2, 192
	s_cbranch_scc1 .Lmap_done_1
	s_add_u32 s99, s2, 64
	s_branch .Lmap_done_1
